# MLA joint path: PV accumulates into o registers in place, removed 32 v_mov_b64 copies per tile; NSA selected-branch lane-uniform mask fast path
# speedup vs baseline: 1.0118x; 1.0118x over previous
; #define LAS __attribute__((address_space(3)))
; __device__ __forceinline__ int crow(int v, int hi) { return (v & 3) + 8 * (v >> 2) + 4 * hi; }
; template <int D, int DV, int MODE, bool HASBIAS, bool JOINT, bool DEFER, class KA, class VA, class PF, class BF, class VF, class NM, class WS, class CB> ...
;     ...
;                 if (HASBIAS) {
; #pragma unroll
;                     for (int a4 = 0; a4 < 4; ++a4) { const int kin0 = sub * 32 + 8 * a4 + 4 * hi; const f32x4 kq = *(const LAS f32x4*)(kp + kin0);
; #pragma unroll
;                         for (int e = 0; e < 4; ++e) s[4 * a4 + e] = s[4 * a4 + e] * c1 + bf(t, kin0 + e, kq[e]); }
;                 }
;                 const bool masked = nm(t, sub);
;                 if (masked) {
; #pragma unroll
;                     for (int v = 0; v < 16; ++v) { const int kin = sub * 32 + crow(v, hi); if (!vf(t, kin)) s[v] = NEGB; }
; __device__ __forceinline__ void nsa_unit(const KP& P, LAS unsigned char* lds, int b, int c, int g, int tid_u) {
;     ...
;         auto vf2 = [&](int t, int kin) -> bool { const int sb = TL[t]; const bool selb = (((sb < 64 ? ms0 : ms1) >> (sb & 63)) & 1ull) != 0ull; return selb && (64 * sb + kin <= tq); };
.LBB0_805:
	s_xor_b64 s[10:11], s[8:9], -1
	s_waitcnt lgkmcnt(0)
	v_pk_fma_f32 v[176:177], v[146:147], v[90:91], v[112:113]
	v_pk_fma_f32 v[102:103], v[150:151], v[102:103], v[116:117]
	v_pk_fma_f32 v[90:91], v[154:155], v[98:99], v[120:121]
	v_pk_fma_f32 v[94:95], v[158:159], v[94:95], v[124:125]
	v_pk_fma_f32 v[178:179], v[148:149], v[100:101], v[114:115]
	v_pk_fma_f32 v[96:97], v[152:153], v[96:97], v[118:119]
	v_pk_fma_f32 v[92:93], v[156:157], v[92:93], v[122:123]
	v_pk_fma_f32 v[88:89], v[132:133], v[88:89], v[108:109]
	s_mov_b32 s8, 0x3e38aa3b
	v_pk_fma_f32 v[50:51], v[50:51], s[8:9], v[94:95] op_sel_hi:[1,0,1]
	v_pk_fma_f32 v[90:91], v[46:47], s[8:9], v[90:91] op_sel_hi:[1,0,1]
	v_pk_fma_f32 v[94:95], v[42:43], s[8:9], v[102:103] op_sel_hi:[1,0,1]
	v_pk_fma_f32 v[98:99], v[38:39], s[8:9], v[176:177] op_sel_hi:[1,0,1]
	v_pk_fma_f32 v[100:101], v[36:37], s[8:9], v[88:89] op_sel_hi:[1,0,1]
	v_pk_fma_f32 v[88:89], v[48:49], s[8:9], v[92:93] op_sel_hi:[1,0,1]
	v_pk_fma_f32 v[92:93], v[44:45], s[8:9], v[96:97] op_sel_hi:[1,0,1]
	v_pk_fma_f32 v[96:97], v[40:41], s[8:9], v[178:179] op_sel_hi:[1,0,1]
	s_and_b64 vcc, exec, s[10:11]
	s_cbranch_vccnz .LBB0_807
	s_cmp_lg_u32 s12, s61
	s_cbranch_scc1 .Lnsa_fm1
	s_lshl_b32 s8, s12, 6
	v_and_b32_e32 v37, v161, v1
	v_and_b32_e32 v36, v160, v2
	v_or_b32_e32 v1, s8, v166
	v_cmp_ne_u64_e32 vcc, 0, v[36:37]
	v_cmp_le_i32_e64 s[42:43], v1, v130
	s_and_b64 s[42:43], vcc, s[42:43]
	v_or_b32_e32 v1, s8, v185
	v_cndmask_b32_e64 v100, v239, v100, s[42:43]
	v_cmp_le_i32_e64 s[42:43], v1, v130
	s_and_b64 s[42:43], vcc, s[42:43]
	v_or_b32_e32 v1, s8, v186
	v_cndmask_b32_e64 v101, v239, v101, s[42:43]
	v_cmp_le_i32_e64 s[42:43], v1, v130
	s_and_b64 s[42:43], vcc, s[42:43]
	v_or_b32_e32 v1, s8, v187
	v_cndmask_b32_e64 v98, v239, v98, s[42:43]
	v_cmp_le_i32_e64 s[42:43], v1, v130
	s_and_b64 s[42:43], vcc, s[42:43]
	v_or_b32_e32 v1, s8, v188
	v_cndmask_b32_e64 v99, v239, v99, s[42:43]
	v_cmp_le_i32_e64 s[42:43], v1, v130
	s_and_b64 s[42:43], vcc, s[42:43]
	v_or_b32_e32 v1, s8, v189
	v_cndmask_b32_e64 v96, v239, v96, s[42:43]
	v_cmp_le_i32_e64 s[42:43], v1, v130
	s_and_b64 s[42:43], vcc, s[42:43]
	v_or_b32_e32 v1, s8, v190
	v_cndmask_b32_e64 v97, v239, v97, s[42:43]
	v_cmp_le_i32_e64 s[42:43], v1, v130
	s_and_b64 s[42:43], vcc, s[42:43]
	v_or_b32_e32 v1, s8, v191
	v_cndmask_b32_e64 v94, v239, v94, s[42:43]
	v_cmp_le_i32_e64 s[42:43], v1, v130
	s_and_b64 s[42:43], vcc, s[42:43]
	v_or_b32_e32 v1, s8, v192
	v_cndmask_b32_e64 v95, v239, v95, s[42:43]
	v_cmp_le_i32_e64 s[42:43], v1, v130
	s_and_b64 s[42:43], vcc, s[42:43]
	v_or_b32_e32 v1, s8, v193
	v_cndmask_b32_e64 v92, v239, v92, s[42:43]
	v_cmp_le_i32_e64 s[42:43], v1, v130
	s_and_b64 s[42:43], vcc, s[42:43]
	v_or_b32_e32 v1, s8, v194
	v_cndmask_b32_e64 v93, v239, v93, s[42:43]
	v_cmp_le_i32_e64 s[42:43], v1, v130
	s_and_b64 s[42:43], vcc, s[42:43]
	v_or_b32_e32 v1, s8, v195
	v_cndmask_b32_e64 v90, v239, v90, s[42:43]
	v_cmp_le_i32_e64 s[42:43], v1, v130
	s_and_b64 s[42:43], vcc, s[42:43]
	v_or_b32_e32 v1, s8, v196
	v_cndmask_b32_e64 v91, v239, v91, s[42:43]
	v_cmp_le_i32_e64 s[42:43], v1, v130
	s_and_b64 s[42:43], vcc, s[42:43]
	v_or_b32_e32 v1, s8, v197
	v_cndmask_b32_e64 v88, v239, v88, s[42:43]
	v_cmp_le_i32_e64 s[42:43], v1, v130
	s_and_b64 s[42:43], vcc, s[42:43]
	v_or_b32_e32 v1, s8, v198
	v_cndmask_b32_e64 v89, v239, v89, s[42:43]
	v_cmp_le_i32_e64 s[42:43], v1, v130
	s_and_b64 s[42:43], vcc, s[42:43]
	v_or_b32_e32 v1, s8, v199
	v_cndmask_b32_e64 v50, v239, v50, s[42:43]
	v_cmp_le_i32_e64 s[42:43], v1, v130
	s_and_b64 vcc, vcc, s[42:43]
	v_cndmask_b32_e32 v51, v239, v51, vcc

; __device__ __forceinline__ float fast_exp2(float x) { return __builtin_amdgcn_exp2f(x); }
; template <int D, int DV, int MODE, bool HASBIAS, bool JOINT, bool DEFER, class KA, class VA, class PF, class BF, class VF, class NM, class WS, class CB> ...
;     ...
;                     if (masked) {
; #pragma unroll
;                         for (int v = 0; v < 16; ++v) { const float p = s[v] > -1e29f ? fast_exp2(s[v] - mn) : 0.f; s[v] = p; sum += p; }
;                     } else {
; #pragma unroll
;                         for (int v = 0; v < 16; ++v) { const float p = fast_exp2(s[v] - mn); s[v] = p; sum += p; }
;                     }
.Lnsa_sum1:
	v_add_f32_e32 v103, 0, v48
	v_add_f32_e32 v103, v1, v103
	v_add_f32_e32 v103, v2, v103
	v_add_f32_e32 v103, v49, v103
	v_add_f32_e32 v103, v46, v103
	v_add_f32_e32 v103, v47, v103
	v_add_f32_e32 v103, v44, v103
	v_add_f32_e32 v103, v45, v103
	v_add_f32_e32 v103, v42, v103
	v_add_f32_e32 v103, v43, v103
	v_add_f32_e32 v103, v40, v103
	v_add_f32_e32 v103, v41, v103
	v_add_f32_e32 v103, v38, v103
	v_add_f32_e32 v103, v39, v103
	v_add_f32_e32 v103, v36, v103
	v_add_f32_e32 v103, v37, v103
	s_cbranch_execz .LBB0_813

; __device__ __forceinline__ float fast_exp2(float x) { return __builtin_amdgcn_exp2f(x); }
; template <int D, int DV, int MODE, bool HASBIAS, bool JOINT, bool DEFER, class KA, class VA, class PF, class BF, class VF, class NM, class WS, class CB> ...
;     ...
;                     if (masked) {
; #pragma unroll
;                         for (int v = 0; v < 16; ++v) { const float p = s[v] > -1e29f ? fast_exp2(s[v] - mn) : 0.f; s[v] = p; sum += p; }
; __device__ __forceinline__ void nsa_unit(const KP& P, LAS unsigned char* lds, int b, int c, int g, int tid_u) {
;     ...
;         auto vf2 = [&](int t, int kin) -> bool { const int sb = TL[t]; const bool selb = (((sb < 64 ? ms0 : ms1) >> (sb & 63)) & 1ull) != 0ull; return selb && (64 * sb + kin <= tq); };
.LBB0_813:
	s_cmp_lg_u32 s12, s61
	s_cbranch_scc1 .Lnsa_fs1
	s_mov_b32 s10, 0xefa18f08
	v_cmp_lt_f32_e32 vcc, s10, v100
	s_nop 1
	v_cndmask_b32_e32 v48, 0, v48, vcc
	v_cmp_lt_f32_e32 vcc, s10, v101
	v_add_f32_e32 v100, 0, v48
	s_nop 0
	v_cndmask_b32_e32 v1, 0, v1, vcc
	v_cmp_lt_f32_e32 vcc, s10, v98
	v_add_f32_e32 v100, v1, v100
	s_nop 0
	v_cndmask_b32_e32 v2, 0, v2, vcc
	v_cmp_lt_f32_e32 vcc, s10, v99
	v_add_f32_e32 v98, v2, v100
	s_nop 0
	v_cndmask_b32_e32 v49, 0, v49, vcc
	v_cmp_lt_f32_e32 vcc, s10, v96
	v_add_f32_e32 v98, v49, v98
	s_nop 0
	v_cndmask_b32_e32 v46, 0, v46, vcc
	v_cmp_lt_f32_e32 vcc, s10, v97
	v_add_f32_e32 v96, v46, v98
	s_nop 0
	v_cndmask_b32_e32 v47, 0, v47, vcc
	v_cmp_lt_f32_e32 vcc, s10, v94
	v_add_f32_e32 v96, v47, v96
	s_nop 0
	v_cndmask_b32_e32 v44, 0, v44, vcc
	v_cmp_lt_f32_e32 vcc, s10, v95
	v_add_f32_e32 v94, v44, v96
	s_nop 0
	v_cndmask_b32_e32 v45, 0, v45, vcc
	v_cmp_lt_f32_e32 vcc, s10, v92
	v_add_f32_e32 v94, v45, v94
	s_nop 0
	v_cndmask_b32_e32 v42, 0, v42, vcc
	v_cmp_lt_f32_e32 vcc, s10, v93
	v_add_f32_e32 v92, v42, v94
	s_nop 0
	v_cndmask_b32_e32 v43, 0, v43, vcc
	v_cmp_lt_f32_e32 vcc, s10, v90
	v_add_f32_e32 v92, v43, v92
	s_nop 0
	v_cndmask_b32_e32 v40, 0, v40, vcc
	v_cmp_lt_f32_e32 vcc, s10, v91
	v_add_f32_e32 v90, v40, v92
	s_nop 0
	v_cndmask_b32_e32 v41, 0, v41, vcc
	v_cmp_lt_f32_e32 vcc, s10, v88
	v_add_f32_e32 v90, v41, v90
	s_nop 0
	v_cndmask_b32_e32 v38, 0, v38, vcc
	v_cmp_lt_f32_e32 vcc, s10, v89
	v_add_f32_e32 v88, v38, v90
	s_nop 0
	v_cndmask_b32_e32 v39, 0, v39, vcc
	v_cmp_lt_f32_e32 vcc, s10, v50
	v_add_f32_e32 v88, v39, v88
	s_nop 0
	v_cndmask_b32_e32 v36, 0, v36, vcc
	v_cmp_lt_f32_e32 vcc, s10, v51
	v_add_f32_e32 v50, v36, v88
	s_nop 0
	v_cndmask_b32_e32 v37, 0, v37, vcc
	v_add_f32_e32 v103, v37, v50
	s_andn2_b64 vcc, exec, s[8:9]
	s_cbranch_vccz .LBB0_810
	s_branch .LBB0_811
.Lnsa_fm1:
	v_and_b32_e32 v37, v161, v1
	v_and_b32_e32 v36, v160, v2
	v_cmp_ne_u64_e32 vcc, 0, v[36:37]
	s_nop 1
	v_cndmask_b32_e32 v100, v239, v100, vcc
	v_cndmask_b32_e32 v101, v239, v101, vcc
	v_cndmask_b32_e32 v98, v239, v98, vcc
	v_cndmask_b32_e32 v99, v239, v99, vcc
	v_cndmask_b32_e32 v96, v239, v96, vcc
	v_cndmask_b32_e32 v97, v239, v97, vcc
	v_cndmask_b32_e32 v94, v239, v94, vcc
	v_cndmask_b32_e32 v95, v239, v95, vcc
	v_cndmask_b32_e32 v92, v239, v92, vcc
	v_cndmask_b32_e32 v93, v239, v93, vcc
	v_cndmask_b32_e32 v90, v239, v90, vcc
	v_cndmask_b32_e32 v91, v239, v91, vcc
	v_cndmask_b32_e32 v88, v239, v88, vcc
	v_cndmask_b32_e32 v89, v239, v89, vcc
	v_cndmask_b32_e32 v50, v239, v50, vcc
	v_cndmask_b32_e32 v51, v239, v51, vcc
	s_branch .LBB0_807
.Lnsa_fs1:
	s_cmp_lt_i32 s12, 64
	s_cselect_b64 s[42:43], -1, 0
	v_cndmask_b32_e64 v176, v70, v68, s[42:43]
	v_cndmask_b32_e64 v177, v71, v69, s[42:43]
	v_lshrrev_b64 v[176:177], s12, v[176:177]
	v_and_b32_e32 v176, 1, v176
	v_cmp_ne_u32_e32 vcc, 0, v176
	s_nop 1
	v_cndmask_b32_e32 v48, 0, v48, vcc
	v_cndmask_b32_e32 v1, 0, v1, vcc
	v_cndmask_b32_e32 v2, 0, v2, vcc
	v_cndmask_b32_e32 v49, 0, v49, vcc
	v_cndmask_b32_e32 v46, 0, v46, vcc
	v_cndmask_b32_e32 v47, 0, v47, vcc
	v_cndmask_b32_e32 v44, 0, v44, vcc
	v_cndmask_b32_e32 v45, 0, v45, vcc
	v_cndmask_b32_e32 v42, 0, v42, vcc
	v_cndmask_b32_e32 v43, 0, v43, vcc
	v_cndmask_b32_e32 v40, 0, v40, vcc
	v_cndmask_b32_e32 v41, 0, v41, vcc
	v_cndmask_b32_e32 v38, 0, v38, vcc
	v_cndmask_b32_e32 v39, 0, v39, vcc
	v_cndmask_b32_e32 v36, 0, v36, vcc
	v_cndmask_b32_e32 v37, 0, v37, vcc
	s_branch .Lnsa_sum1

; #define LAS __attribute__((address_space(3)))
; __device__ __forceinline__ int crow(int v, int hi) { return (v & 3) + 8 * (v >> 2) + 4 * hi; }
; template <int D, int DV, int MODE, bool HASBIAS, bool JOINT, bool DEFER, class KA, class VA, class PF, class BF, class VF, class NM, class WS, class CB> ...
;     ...
;                 if (HASBIAS) {
; #pragma unroll
;                     for (int a4 = 0; a4 < 4; ++a4) { const int kin0 = sub * 32 + 8 * a4 + 4 * hi; const f32x4 kq = *(const LAS f32x4*)(kp + kin0);
; #pragma unroll
;                         for (int e = 0; e < 4; ++e) s[4 * a4 + e] = s[4 * a4 + e] * c1 + bf(t, kin0 + e, kq[e]); }
;                 }
;                 const bool masked = nm(t, sub);
;                 if (masked) {
; #pragma unroll
;                     for (int v = 0; v < 16; ++v) { const int kin = sub * 32 + crow(v, hi); if (!vf(t, kin)) s[v] = NEGB; }
; __device__ __forceinline__ void nsa_unit(const KP& P, LAS unsigned char* lds, int b, int c, int g, int tid_u) {
;     ...
;         auto vf2 = [&](int t, int kin) -> bool { const int sb = TL[t]; const bool selb = (((sb < 64 ? ms0 : ms1) >> (sb & 63)) & 1ull) != 0ull; return selb && (64 * sb + kin <= tq); };
.LBB0_818:
	s_xor_b64 s[10:11], s[8:9], -1
	s_waitcnt lgkmcnt(0)
	v_pk_fma_f32 v[176:177], v[146:147], v[90:91], v[112:113]
	v_pk_fma_f32 v[102:103], v[150:151], v[102:103], v[116:117]
	v_pk_fma_f32 v[90:91], v[154:155], v[98:99], v[120:121]
	v_pk_fma_f32 v[94:95], v[158:159], v[94:95], v[124:125]
	v_pk_fma_f32 v[178:179], v[148:149], v[100:101], v[114:115]
	v_pk_fma_f32 v[96:97], v[152:153], v[96:97], v[118:119]
	v_pk_fma_f32 v[92:93], v[156:157], v[92:93], v[122:123]
	v_pk_fma_f32 v[88:89], v[132:133], v[88:89], v[108:109]
	s_mov_b32 s8, 0x3e38aa3b
	v_pk_fma_f32 v[50:51], v[50:51], s[8:9], v[94:95] op_sel_hi:[1,0,1]
	v_pk_fma_f32 v[90:91], v[46:47], s[8:9], v[90:91] op_sel_hi:[1,0,1]
	v_pk_fma_f32 v[94:95], v[42:43], s[8:9], v[102:103] op_sel_hi:[1,0,1]
	v_pk_fma_f32 v[98:99], v[38:39], s[8:9], v[176:177] op_sel_hi:[1,0,1]
	v_pk_fma_f32 v[100:101], v[36:37], s[8:9], v[88:89] op_sel_hi:[1,0,1]
	v_pk_fma_f32 v[88:89], v[48:49], s[8:9], v[92:93] op_sel_hi:[1,0,1]
	v_pk_fma_f32 v[92:93], v[44:45], s[8:9], v[96:97] op_sel_hi:[1,0,1]
	v_pk_fma_f32 v[96:97], v[40:41], s[8:9], v[178:179] op_sel_hi:[1,0,1]
	s_and_b64 vcc, exec, s[10:11]
	s_cbranch_vccnz .LBB0_820
	s_cmp_lg_u32 s12, s61
	s_cbranch_scc1 .Lnsa_fm2
	v_lshrrev_b64 v[36:37], s12, v[160:161]
	v_and_b32_e32 v1, 1, v36
	s_lshl_b32 s8, s12, 6
	v_cmp_eq_u32_e32 vcc, 1, v1
	v_or_b32_e32 v1, s8, v200
	v_cmp_le_i32_e64 s[42:43], v1, v130
	s_and_b64 s[42:43], vcc, s[42:43]
	v_or_b32_e32 v1, s8, v201
	v_cndmask_b32_e64 v100, v239, v100, s[42:43]
	v_cmp_le_i32_e64 s[42:43], v1, v130
	s_and_b64 s[42:43], vcc, s[42:43]
	v_or_b32_e32 v1, s8, v202
	v_cndmask_b32_e64 v101, v239, v101, s[42:43]
	v_cmp_le_i32_e64 s[42:43], v1, v130
	s_and_b64 s[42:43], vcc, s[42:43]
	v_or_b32_e32 v1, s8, v203
	v_cndmask_b32_e64 v98, v239, v98, s[42:43]
	v_cmp_le_i32_e64 s[42:43], v1, v130
	s_and_b64 s[42:43], vcc, s[42:43]
	v_or_b32_e32 v1, s8, v204
	v_cndmask_b32_e64 v99, v239, v99, s[42:43]
	v_cmp_le_i32_e64 s[42:43], v1, v130
	s_and_b64 s[42:43], vcc, s[42:43]
	v_or_b32_e32 v1, s8, v205
	v_cndmask_b32_e64 v96, v239, v96, s[42:43]
	v_cmp_le_i32_e64 s[42:43], v1, v130
	s_and_b64 s[42:43], vcc, s[42:43]
	v_or_b32_e32 v1, s8, v206
	v_cndmask_b32_e64 v97, v239, v97, s[42:43]
	v_cmp_le_i32_e64 s[42:43], v1, v130
	s_and_b64 s[42:43], vcc, s[42:43]
	v_or_b32_e32 v1, s8, v207
	v_cndmask_b32_e64 v94, v239, v94, s[42:43]
	v_cmp_le_i32_e64 s[42:43], v1, v130
	s_and_b64 s[42:43], vcc, s[42:43]
	v_or_b32_e32 v1, s8, v210
	v_cndmask_b32_e64 v95, v239, v95, s[42:43]
	v_cmp_le_i32_e64 s[42:43], v1, v130
	s_and_b64 s[42:43], vcc, s[42:43]
	v_or_b32_e32 v1, s8, v211
	v_cndmask_b32_e64 v92, v239, v92, s[42:43]
	v_cmp_le_i32_e64 s[42:43], v1, v130
	s_and_b64 s[42:43], vcc, s[42:43]
	v_or_b32_e32 v1, s8, v212
	v_cndmask_b32_e64 v93, v239, v93, s[42:43]
	v_cmp_le_i32_e64 s[42:43], v1, v130
	s_and_b64 s[42:43], vcc, s[42:43]
	v_or_b32_e32 v1, s8, v213
	v_cndmask_b32_e64 v90, v239, v90, s[42:43]
	v_cmp_le_i32_e64 s[42:43], v1, v130
	s_and_b64 s[42:43], vcc, s[42:43]
	v_or_b32_e32 v1, s8, v214
	v_cndmask_b32_e64 v91, v239, v91, s[42:43]
	v_cmp_le_i32_e64 s[42:43], v1, v130
	s_and_b64 s[42:43], vcc, s[42:43]
	v_or_b32_e32 v1, s8, v215
	v_cndmask_b32_e64 v88, v239, v88, s[42:43]
	v_cmp_le_i32_e64 s[42:43], v1, v130
	s_and_b64 s[42:43], vcc, s[42:43]
	v_or_b32_e32 v1, s8, v216
	v_cndmask_b32_e64 v89, v239, v89, s[42:43]
	v_cmp_le_i32_e64 s[42:43], v1, v130
	s_and_b64 s[42:43], vcc, s[42:43]
	v_or_b32_e32 v1, s8, v217
	v_cndmask_b32_e64 v50, v239, v50, s[42:43]
	v_cmp_le_i32_e64 s[42:43], v1, v130
	s_and_b64 vcc, vcc, s[42:43]
	v_cndmask_b32_e32 v51, v239, v51, vcc

; __device__ __forceinline__ int crow(int v, int hi) { return (v & 3) + 8 * (v >> 2) + 4 * hi; }
; template <int D, int DV, int MODE, bool HASBIAS, bool JOINT, bool DEFER, class KA, class VA, class PF, class BF, class VF, class NM, class WS, class CB> ...
;     ...
;                 const bool masked = nm(t, sub);
;                 if (masked) {
; #pragma unroll
;                     for (int v = 0; v < 16; ++v) { const int kin = sub * 32 + crow(v, hi); if (!vf(t, kin)) s[v] = NEGB; }
; __device__ __forceinline__ void nsa_unit(const KP& P, LAS unsigned char* lds, int b, int c, int g, int tid_u) {
;     ...
;         auto vf2 = [&](int t, int kin) -> bool { const int sb = TL[t]; const bool selb = (((sb < 64 ? ms0 : ms1) >> (sb & 63)) & 1ull) != 0ull; return selb && (64 * sb + kin <= tq); };
.Lnsa_fm2:
	v_lshrrev_b64 v[36:37], s12, v[160:161]
	v_and_b32_e32 v1, 1, v36
	v_cmp_eq_u32_e32 vcc, 1, v1
	s_nop 1
	v_cndmask_b32_e32 v100, v239, v100, vcc
	v_cndmask_b32_e32 v101, v239, v101, vcc
	v_cndmask_b32_e32 v98, v239, v98, vcc
	v_cndmask_b32_e32 v99, v239, v99, vcc
	v_cndmask_b32_e32 v96, v239, v96, vcc
	v_cndmask_b32_e32 v97, v239, v97, vcc
	v_cndmask_b32_e32 v94, v239, v94, vcc
	v_cndmask_b32_e32 v95, v239, v95, vcc
	v_cndmask_b32_e32 v92, v239, v92, vcc
	v_cndmask_b32_e32 v93, v239, v93, vcc
	v_cndmask_b32_e32 v90, v239, v90, vcc
	v_cndmask_b32_e32 v91, v239, v91, vcc
	v_cndmask_b32_e32 v88, v239, v88, vcc
	v_cndmask_b32_e32 v89, v239, v89, vcc
	v_cndmask_b32_e32 v50, v239, v50, vcc
	v_cndmask_b32_e32 v51, v239, v51, vcc
	s_branch .LBB0_820

; __device__ __forceinline__ unsigned cvt_pk_bf16(float lo, float hi) { unsigned r; asm volatile("v_cvt_pk_bf16_f32 %0, %1, %2" : "=v"(r) : "v"(lo), "v"(hi)); return r; }
; #define LAS __attribute__((address_space(3)))
; __device__ __forceinline__ float fast_exp2(float x) { return __builtin_amdgcn_exp2f(x); }
; template <int DV32>
; __device__ __forceinline__ void pv_sub(f32x16 (&o)[DV32], const LAS unsigned char* Vt, int vs, int sub, const f32x16& p, int r32, int hi) {
;     ...
;     for (int kb = 0; kb < 2; ++kb) {
;         u32x4 pw; pw.x = cvt_pk_bf16(p[8 * kb + 0], p[8 * kb + 1]); pw.y = cvt_pk_bf16(p[8 * kb + 2], p[8 * kb + 3]); pw.z = cvt_pk_bf16(p[8 * kb + 4], p[8 * kb + 5]); pw.w = cvt_pk_bf16(p[8 * kb + 6], p[8 * kb + 7]);
;         const bf16x8 pf = __builtin_bit_cast(bf16x8, pw);
; #pragma unroll
;         for (int i = 0; i < DV32; ++i) {
;             const bf16x8 vf = *(const LAS bf16x8*)(Vt + (32 * i + r32) * vs + sub * 64 + kb * 32 + hi * 16);
;             o[i] = __builtin_amdgcn_mfma_f32_32x32x16_bf16(vf, pf, o[i], 0, 0, 0);
;         }
; template <int D, int DV, int MODE, bool HASBIAS, bool JOINT, bool DEFER, class KA, class VA, class PF, class BF, class VF, class NM, class WS, class CB> ...
;     ...
;             if (grow) {
;                 const float alpha = fast_exp2(m - mn); l *= alpha;
;                 if (MODE == 0) {
; #pragma unroll
;                     for (int i = 0; i < DV / 32; ++i)
; #pragma unroll
;                         for (int v = 0; v < 16; ++v) o[i][v] *= alpha;
;                 }
;             }
;             l += sum0 + sum1; m = mn;
;             if (MODE == 0) {
;                 if (defer_wave) { pp0 = pack8(s0, 0); pp1 = pack8(s0, 1); pp2 = pack8(s1, 0); pp3 = pack8(s1, 1); pend = vslot; }
;                 else { pv_sub<DV / 32>(o, curv, VS, 0, s0, r32, hi); pv_sub<DV / 32>(o, curv, VS, 1, s1, r32, hi); }
.LBB0_1023:
	s_andn2_b64 vcc, exec, s[10:11]
	v_mov_b32_e32 v192, v191
	s_cbranch_vccnz .LBB0_1025
	v_sub_f32_e32 v1, v189, v1
	v_exp_f32_e32 v36, v1
	s_nop 0
	v_mul_f32_e32 v192, v191, v36
	v_pk_mul_f32 v[34:35], v[34:35], v[36:37] op_sel_hi:[1,0]
	v_pk_mul_f32 v[32:33], v[32:33], v[36:37] op_sel_hi:[1,0]
	v_pk_mul_f32 v[30:31], v[30:31], v[36:37] op_sel_hi:[1,0]
	v_pk_mul_f32 v[28:29], v[28:29], v[36:37] op_sel_hi:[1,0]
	v_pk_mul_f32 v[26:27], v[26:27], v[36:37] op_sel_hi:[1,0]
	v_pk_mul_f32 v[24:25], v[24:25], v[36:37] op_sel_hi:[1,0]
	v_pk_mul_f32 v[22:23], v[22:23], v[36:37] op_sel_hi:[1,0]
	v_pk_mul_f32 v[20:21], v[20:21], v[36:37] op_sel_hi:[1,0]
	v_pk_mul_f32 v[18:19], v[18:19], v[36:37] op_sel_hi:[1,0]
	v_pk_mul_f32 v[16:17], v[16:17], v[36:37] op_sel_hi:[1,0]
	v_pk_mul_f32 v[14:15], v[14:15], v[36:37] op_sel_hi:[1,0]
	v_pk_mul_f32 v[12:13], v[12:13], v[36:37] op_sel_hi:[1,0]
	v_pk_mul_f32 v[10:11], v[10:11], v[36:37] op_sel_hi:[1,0]
	v_pk_mul_f32 v[8:9], v[8:9], v[36:37] op_sel_hi:[1,0]
	v_pk_mul_f32 v[6:7], v[6:7], v[36:37] op_sel_hi:[1,0]
	v_pk_mul_f32 v[4:5], v[4:5], v[36:37] op_sel_hi:[1,0]
.LBB0_1025:
	v_add_f32_e32 v1, v168, v169
	v_add_f32_e32 v192, v1, v192
	v_add_u32_e32 v1, v175, v184
	v_cvt_pk_bf16_f32 v194, v151, v157
	v_cvt_pk_bf16_f32 v195, v153, v161
	v_cvt_pk_bf16_f32 v196, v155, v165
	v_cvt_pk_bf16_f32 v197, v159, v167
	ds_read_b128 v[198:201], v1 offset:26624
	s_mov_b64 s[10:11], 0
	s_waitcnt lgkmcnt(0)
	v_mfma_f32_32x32x16_bf16 v[4:19], v[198:201], v[194:197], v[4:19]
	ds_read_b128 v[198:201], v1 offset:31232
	s_waitcnt lgkmcnt(0)
	v_mfma_f32_32x32x16_bf16 v[20:35], v[198:201], v[194:197], v[20:35]
	v_cvt_pk_bf16_f32 v194, v69, v75
	v_cvt_pk_bf16_f32 v195, v71, v79
	v_cvt_pk_bf16_f32 v196, v73, v81
	v_cvt_pk_bf16_f32 v197, v77, v83
	ds_read_b128 v[198:201], v1 offset:26656
	s_waitcnt lgkmcnt(0)
	v_mfma_f32_32x32x16_bf16 v[4:19], v[198:201], v[194:197], v[4:19]
	ds_read_b128 v[198:201], v1 offset:31264
	v_cvt_pk_bf16_f32 v150, v150, v156
	v_cvt_pk_bf16_f32 v151, v152, v160
	v_cvt_pk_bf16_f32 v152, v154, v164
	v_cvt_pk_bf16_f32 v153, v158, v166
	ds_read_b128 v[154:157], v1 offset:26688
	s_waitcnt lgkmcnt(0)
	v_mfma_f32_32x32x16_bf16 v[4:19], v[154:157], v[150:153], v[4:19]
	ds_read_b128 v[154:157], v1 offset:31296
	v_cvt_pk_bf16_f32 v68, v68, v74
	v_cvt_pk_bf16_f32 v69, v70, v78
	v_cvt_pk_bf16_f32 v70, v72, v80
	v_cvt_pk_bf16_f32 v71, v76, v82
	ds_read_b128 v[72:75], v1 offset:26720
	v_mfma_f32_32x32x16_bf16 v[20:35], v[198:201], v[194:197], v[20:35]
	s_waitcnt lgkmcnt(0)
	v_mfma_f32_32x32x16_bf16 v[4:19], v[72:75], v[68:71], v[4:19]
	ds_read_b128 v[72:75], v1 offset:31328
	v_mfma_f32_32x32x16_bf16 v[20:35], v[154:157], v[150:153], v[20:35]
	s_waitcnt lgkmcnt(0)
	v_mfma_f32_32x32x16_bf16 v[20:35], v[72:75], v[68:71], v[20:35]

; __device__ __forceinline__ unsigned cvt_pk_bf16(float lo, float hi) { unsigned r; asm volatile("v_cvt_pk_bf16_f32 %0, %1, %2" : "=v"(r) : "v"(lo), "v"(hi)); return r; }
; #define LAS __attribute__((address_space(3)))
; __device__ __forceinline__ float fast_exp2(float x) { return __builtin_amdgcn_exp2f(x); }
; template <int DV32>
; __device__ __forceinline__ void pv_sub(f32x16 (&o)[DV32], const LAS unsigned char* Vt, int vs, int sub, const f32x16& p, int r32, int hi) {
;     ...
;     for (int kb = 0; kb < 2; ++kb) {
;         u32x4 pw; pw.x = cvt_pk_bf16(p[8 * kb + 0], p[8 * kb + 1]); pw.y = cvt_pk_bf16(p[8 * kb + 2], p[8 * kb + 3]); pw.z = cvt_pk_bf16(p[8 * kb + 4], p[8 * kb + 5]); pw.w = cvt_pk_bf16(p[8 * kb + 6], p[8 * kb + 7]);
;         const bf16x8 pf = __builtin_bit_cast(bf16x8, pw);
; #pragma unroll
;         for (int i = 0; i < DV32; ++i) {
;             const bf16x8 vf = *(const LAS bf16x8*)(Vt + (32 * i + r32) * vs + sub * 64 + kb * 32 + hi * 16);
;             o[i] = __builtin_amdgcn_mfma_f32_32x32x16_bf16(vf, pf, o[i], 0, 0, 0);
;         }
; template <int D, int DV, int MODE, bool HASBIAS, bool JOINT, bool DEFER, class KA, class VA, class PF, class BF, class VF, class NM, class WS, class CB> ...
;     ...
;             if (grow) {
;                 const float alpha = fast_exp2(m - mn); l *= alpha;
;                 if (MODE == 0) {
; #pragma unroll
;                     for (int i = 0; i < DV / 32; ++i)
; #pragma unroll
;                         for (int v = 0; v < 16; ++v) o[i][v] *= alpha;
;                 }
;             }
;             l += sum0 + sum1; m = mn;
;             if (MODE == 0) {
;                 if (defer_wave) { pp0 = pack8(s0, 0); pp1 = pack8(s0, 1); pp2 = pack8(s1, 0); pp3 = pack8(s1, 1); pend = vslot; }
;                 else { pv_sub<DV / 32>(o, curv, VS, 0, s0, r32, hi); pv_sub<DV / 32>(o, curv, VS, 1, s1, r32, hi); }
.LBB0_1079:
	s_andn2_b64 vcc, exec, s[10:11]
	v_mov_b32_e32 v191, v192
	s_cbranch_vccnz .LBB0_1081
	v_sub_f32_e32 v1, v190, v1
	v_exp_f32_e32 v36, v1
	s_nop 0
	v_mul_f32_e32 v191, v192, v36
	v_pk_mul_f32 v[34:35], v[34:35], v[36:37] op_sel_hi:[1,0]
	v_pk_mul_f32 v[32:33], v[32:33], v[36:37] op_sel_hi:[1,0]
	v_pk_mul_f32 v[30:31], v[30:31], v[36:37] op_sel_hi:[1,0]
	v_pk_mul_f32 v[28:29], v[28:29], v[36:37] op_sel_hi:[1,0]
	v_pk_mul_f32 v[26:27], v[26:27], v[36:37] op_sel_hi:[1,0]
	v_pk_mul_f32 v[24:25], v[24:25], v[36:37] op_sel_hi:[1,0]
	v_pk_mul_f32 v[22:23], v[22:23], v[36:37] op_sel_hi:[1,0]
	v_pk_mul_f32 v[20:21], v[20:21], v[36:37] op_sel_hi:[1,0]
	v_pk_mul_f32 v[18:19], v[18:19], v[36:37] op_sel_hi:[1,0]
	v_pk_mul_f32 v[16:17], v[16:17], v[36:37] op_sel_hi:[1,0]
	v_pk_mul_f32 v[14:15], v[14:15], v[36:37] op_sel_hi:[1,0]
	v_pk_mul_f32 v[12:13], v[12:13], v[36:37] op_sel_hi:[1,0]
	v_pk_mul_f32 v[10:11], v[10:11], v[36:37] op_sel_hi:[1,0]
	v_pk_mul_f32 v[8:9], v[8:9], v[36:37] op_sel_hi:[1,0]
	v_pk_mul_f32 v[6:7], v[6:7], v[36:37] op_sel_hi:[1,0]
	v_pk_mul_f32 v[4:5], v[4:5], v[36:37] op_sel_hi:[1,0]
.LBB0_1081:
	v_add_f32_e32 v1, v168, v169
	v_add_f32_e32 v191, v1, v191
	v_add_u32_e32 v1, v175, v184
	v_cvt_pk_bf16_f32 v194, v151, v157
	v_cvt_pk_bf16_f32 v195, v153, v161
	v_cvt_pk_bf16_f32 v196, v155, v165
	v_cvt_pk_bf16_f32 v197, v159, v167
	ds_read_b128 v[198:201], v1 offset:35840
	s_mov_b64 s[10:11], 0
	s_waitcnt lgkmcnt(0)
	v_mfma_f32_32x32x16_bf16 v[4:19], v[198:201], v[194:197], v[4:19]
	ds_read_b128 v[198:201], v1 offset:40448
	s_waitcnt lgkmcnt(0)
	v_mfma_f32_32x32x16_bf16 v[20:35], v[198:201], v[194:197], v[20:35]
	v_cvt_pk_bf16_f32 v194, v69, v75
	v_cvt_pk_bf16_f32 v195, v71, v79
	v_cvt_pk_bf16_f32 v196, v73, v81
	v_cvt_pk_bf16_f32 v197, v77, v83
	ds_read_b128 v[198:201], v1 offset:35872
	s_waitcnt lgkmcnt(0)
	v_mfma_f32_32x32x16_bf16 v[4:19], v[198:201], v[194:197], v[4:19]
	ds_read_b128 v[198:201], v1 offset:40480
	v_cvt_pk_bf16_f32 v150, v150, v156
	v_cvt_pk_bf16_f32 v151, v152, v160
	v_cvt_pk_bf16_f32 v152, v154, v164
	v_cvt_pk_bf16_f32 v153, v158, v166
	ds_read_b128 v[154:157], v1 offset:35904
	s_waitcnt lgkmcnt(0)
	v_mfma_f32_32x32x16_bf16 v[4:19], v[154:157], v[150:153], v[4:19]
	ds_read_b128 v[154:157], v1 offset:40512
	v_cvt_pk_bf16_f32 v68, v68, v74
	v_cvt_pk_bf16_f32 v69, v70, v78
	v_cvt_pk_bf16_f32 v70, v72, v80
	v_cvt_pk_bf16_f32 v71, v76, v82
	ds_read_b128 v[72:75], v1 offset:35936
	v_mfma_f32_32x32x16_bf16 v[20:35], v[198:201], v[194:197], v[20:35]
	s_waitcnt lgkmcnt(0)
	v_mfma_f32_32x32x16_bf16 v[4:19], v[72:75], v[68:71], v[4:19]
	ds_read_b128 v[72:75], v1 offset:40544
	v_mfma_f32_32x32x16_bf16 v[20:35], v[154:157], v[150:153], v[20:35]
	s_waitcnt lgkmcnt(0)
	v_mfma_f32_32x32x16_bf16 v[20:35], v[72:75], v[68:71], v[20:35]
